# v15 with the steady KV-loop head aligned to 64 bytes (code placement check)
# speedup vs baseline: 1.0079x; 1.0079x over previous
; #define SBAR() __builtin_amdgcn_sched_barrier(0)
; #define RESC(a) do { if (__any((a) < 1.f)) { if (hi == 0) al_l[r32] = (a); asm volatile("s_waitcnt lgkmcnt(0)" ::: "memory"); \
;     _Pragma("unroll") for (int d = 0; d < 4; ++d) _Pragma("unroll") for (int r = 0; r < 16; ++r) o[d][r] *= al_l[crow(r, hi)]; } } while (0)
; #define LBAR() do { asm volatile("s_waitcnt lgkmcnt(0)" ::: "memory"); __builtin_amdgcn_s_barrier(); asm volatile("" ::: "memory"); } while (0)
; __device__ __forceinline__ void attn_unit(const bf16_t* __restrict__ Qb, const bf16_t* __restrict__ Kn, const bf16_t* __restrict__ Vh, const bf16_t* __restrict__ Kr,
;                                           bf16_t* GO, int seq, char* lds, const int tid) {
;     ...
;   for (int j = 1; j + 1 < NT; j += 2) {
;     const int bp = bc == 0 ? 2 : bc - 1, bn = bc == 2 ? 0 : bc + 1;
;     SBAR(); qkt(pB0, pB1, K_lds + bc * SHM_K, qr, qrl, r32, hi);
;     finishSM(pA0, pA1, alA, l_reg, pa0, pa1, pa2, pa3); SBAR();
;     SWRITE(bn, 0); SLOAD(0, (j + 2) * KVBLK); SBAR();
;     pv_d0(o, vb0 + bp * SHM_V, pa0, pa1, pa2, pa3); partialSM(pB0, pB1, m_reg, mnB, alB);
;     RESC(alB); LBAR();
;     SBAR(); qkt(pA0, pA1, K_lds + bn * SHM_K, qr, qrl, r32, hi);
;     finishSM(pB0, pB1, alB, l_reg, pa0, pa1, pa2, pa3); SBAR();
;     SWRITE(bp, 0); if (j + 3 < NT) SLOAD(0, (j + 3) * KVBLK); SBAR();
;     pv_d0(o, vb0 + bc * SHM_V, pa0, pa1, pa2, pa3); partialSM(pA0, pA1, m_reg, mnA, alA);
;     RESC(alA); LBAR();
;     bc = bp;
;   }
.Lattn_skip_rs2p:
	s_and_b64 vcc, exec, s[28:29]
	s_cbranch_vccnz .LBB0_1163
	s_mov_b32 s76, s30
	s_mov_b32 s30, s100
	s_mov_b32 s18, s101
	v_mov_b32_e32 v209, v213
	.p2align 6
